# v013 plus counted waits in the attention unit prologues: first QK block no longer waits for the just-issued tile-2 DMA, attention-A sink load consumed after the first counted wait
# baseline (speedup 1.0000x reference)
; #define AT_BAR() do { asm volatile("s_waitcnt lgkmcnt(0)" ::: "memory"); __builtin_amdgcn_s_barrier(); asm volatile("" ::: "memory"); } while (0)
; #define AT_LOADV(t, sl) do { const int m0_ = AT_M0(t); LAS unsigned char* vd_ = lds + AT_V0 + (sl) * AT_VB; \
;         _Pragma("unroll") for (int i = 0; i < NVL; ++i) { const int piece = wave + 8 * i; const int row = 8 * piece + (lane >> 3), c16 = (lane & 7) ^ ((row >> 1) & 7); \
;             AT_DMA(vbase + (size_t)row * MT + m0_ + 8 * c16, vd_ + 1024 * piece); } } while (0)
; #define AT_VMW(n) asm volatile("s_waitcnt vmcnt(%0)" :: "n"(n) : "memory")
; template <int DQ, int DV, bool WINDOW, bool GQA = false> ...
;     ...
;         bf16x8 qf[NKS];
;         { const bf16* qp = Q + (size_t)(mqw + r32) * ldq + hq * DQ + 8 * hh;
; #pragma unroll
;           for (int ks = 0; ks < NKS; ++ks) qf[ks] = *(const bf16x8*)(qp + 16 * ks); }
;         float m_run, l_run;
;         m_run = 0.f; l_run = (sink && hh == 0) ? __builtin_amdgcn_exp2f(sink[hq] * LOG2E) : 0.f;
;         f32x16 o[NV];
; #pragma unroll
;         for (int v = 0; v < NV; ++v)
; #pragma unroll
;             for (int i = 0; i < 16; ++i) o[v][i] = 0.f;
;         const bf16* kbase = K1 + (size_t)(hq >> kshift) * 64;
;         const bf16* vbase = Vt + (size_t)((hq >> vshift) * DV) * MT;
;         bf16x8 pf[2]; f32x16 s1k; bool pact = true;
; #pragma unroll
;         for (int i = 0; i < 16; ++i) s1k[i] = 0.f;
;     ...
;         AT_LOADK(0, 0); AT_LOADV(0, 0); AT_LOADK(1, 1); AT_LOADV(1, 1); AT_VMW(NKL + NVL); AT_BAR();
;         if (grp == 0) {
.LBB0_582:
	s_lshl_b32 s42, s34, 8
	s_and_b32 s48, s40, 15
	s_add_i32 s26, s42, 0x8000
	s_lshl_b32 s34, s34, 12
	s_and_b64 s[36:37], exec, s[36:37]
	s_cselect_b32 s27, s26, s34
	s_add_i32 s27, s27, s35
	v_add_u32_e32 v118, s27, v134
	v_mov_b64_e32 v[0:1], s[16:17]
	v_mad_i64_i32 v[0:1], s[36:37], v118, s90, v[0:1]
	s_mul_i32 s44, s48, 0xc0
	v_lshl_add_u64 v[0:1], v[0:1], 0, s[44:45]
	v_lshl_add_u64 v[0:1], v[0:1], 0, v[112:113]
	global_load_dwordx4 v[80:83], v[0:1], off
	global_load_dwordx4 v[84:87], v[0:1], off offset:32
	global_load_dwordx4 v[88:91], v[0:1], off offset:64
	global_load_dwordx4 v[92:95], v[0:1], off offset:96
	global_load_dwordx4 v[96:99], v[0:1], off offset:128
	global_load_dwordx4 v[100:103], v[0:1], off offset:160
	s_lshl_b32 s27, s48, 7
	s_add_u32 s46, s1, s27
	v_add_u32_e32 v2, s26, v135
	s_addc_u32 s47, s2, 0
	v_ashrrev_i32_e32 v3, 31, v2
	s_and_saveexec_b64 s[36:37], s[8:9]
	s_xor_b64 s[36:37], exec, s[36:37]
	v_lshlrev_b64 v[0:1], 6, v[2:3]
	v_lshl_add_u64 v[0:1], v[104:105], 0, v[0:1]
	v_lshl_add_u64 v[0:1], v[0:1], 0, s[74:75]
	s_andn2_saveexec_b64 s[36:37], s[36:37]
	v_lshlrev_b64 v[0:1], 11, v[2:3]
	v_lshl_add_u64 v[0:1], s[46:47], 0, v[0:1]
	v_lshl_add_u64 v[0:1], v[106:107], 1, v[0:1]
	s_or_b64 exec, exec, s[36:37]
	s_mov_b32 m0, s19
	v_add_u32_e32 v2, s26, v136
	global_load_lds_dwordx4 v[0:1], off
	v_ashrrev_i32_e32 v3, 31, v2
	s_and_saveexec_b64 s[36:37], s[12:13]
	s_xor_b64 s[36:37], exec, s[36:37]
	v_lshlrev_b64 v[0:1], 6, v[2:3]
	v_lshl_add_u64 v[0:1], v[108:109], 0, v[0:1]
	v_lshl_add_u64 v[0:1], v[0:1], 0, s[74:75]
	s_andn2_saveexec_b64 s[36:37], s[36:37]
	v_lshlrev_b64 v[0:1], 11, v[2:3]
	v_lshl_add_u64 v[0:1], s[46:47], 0, v[0:1]
	v_lshl_add_u64 v[0:1], v[110:111], 1, v[0:1]
	s_or_b64 exec, exec, s[36:37]
	s_add_i32 s35, s31, 0
	s_mul_i32 s44, s48, 0x440000
	s_mov_b32 m0, s35
	v_lshl_add_u64 v[120:121], v[114:115], 0, s[44:45]
	s_ashr_i32 s27, s26, 31
	global_load_lds_dwordx4 v[0:1], off
	v_lshl_add_u64 v[0:1], s[26:27], 1, v[120:121]
	v_mov_b32_e32 v117, v113
	v_lshl_add_u64 v[0:1], v[0:1], 0, v[116:117]
	s_mov_b32 m0, s30
	s_add_i32 s36, s42, 0x8040
	global_load_lds_dwordx4 v[0:1], off
	v_add_u32_e32 v2, s36, v135
	v_ashrrev_i32_e32 v3, 31, v2
	s_and_saveexec_b64 s[40:41], s[8:9]
	s_xor_b64 s[40:41], exec, s[40:41]
	v_lshlrev_b64 v[0:1], 6, v[2:3]
	v_lshl_add_u64 v[0:1], v[104:105], 0, v[0:1]
	v_lshl_add_u64 v[0:1], v[0:1], 0, s[74:75]
	s_andn2_saveexec_b64 s[40:41], s[40:41]
	v_lshlrev_b64 v[0:1], 11, v[2:3]
	v_lshl_add_u64 v[0:1], s[46:47], 0, v[0:1]
	v_lshl_add_u64 v[0:1], v[106:107], 1, v[0:1]
	s_or_b64 exec, exec, s[40:41]
	s_mov_b32 m0, s33
	v_add_u32_e32 v2, s36, v136
	global_load_lds_dwordx4 v[0:1], off
	v_ashrrev_i32_e32 v3, 31, v2
	s_and_saveexec_b64 s[40:41], s[12:13]
	s_xor_b64 s[40:41], exec, s[40:41]
	v_lshlrev_b64 v[0:1], 6, v[2:3]
	v_lshl_add_u64 v[0:1], v[108:109], 0, v[0:1]
	v_lshl_add_u64 v[0:1], v[0:1], 0, s[74:75]
	s_andn2_saveexec_b64 s[40:41], s[40:41]
	v_lshlrev_b64 v[0:1], 11, v[2:3]
	v_lshl_add_u64 v[0:1], s[46:47], 0, v[0:1]
	v_lshl_add_u64 v[0:1], v[110:111], 1, v[0:1]
	s_or_b64 exec, exec, s[40:41]
	s_add_i32 m0, s35, 0x3000
	s_ashr_i32 s37, s36, 31
	global_load_lds_dwordx4 v[0:1], off
	v_lshl_add_u64 v[0:1], s[36:37], 1, v[120:121]
	v_mov_b32_e32 v117, v113
	v_lshl_add_u64 v[0:1], v[0:1], 0, v[116:117]
	s_mov_b32 m0, s38
	s_mov_b64 s[36:37], -1
	global_load_lds_dwordx4 v[0:1], off
	s_waitcnt vmcnt(3)
	s_waitcnt lgkmcnt(0)
	s_barrier
	s_and_b64 vcc, exec, s[28:29]
	s_cbranch_vccz .LBB0_636
; #define AT_LOADV(t, sl) do { const int m0_ = AT_M0(t); LAS unsigned char* vd_ = lds + AT_V0 + (sl) * AT_VB; \
;         _Pragma("unroll") for (int i = 0; i < NVL; ++i) { const int piece = wave + 8 * i; const int row = 8 * piece + (lane >> 3), c16 = (lane & 7) ^ ((row >> 1) & 7); \
;             AT_DMA(vbase + (size_t)row * MT + m0_ + 8 * c16, vd_ + 1024 * piece); } } while (0)
; template <int DQ, int DV, bool WINDOW, bool GQA = false> ...
;     ...
;                 const bool deep = t + 2 < nt;
;                 if (deep) { AT_LOADK(t + 2, k2_); AT_LOADV(t + 2, (t + 2) & 3); }
;                 AT_QKS(t, k0_);
	s_add_i32 s36, s42, 0x8080
	v_add_u32_e32 v2, s36, v135
	v_ashrrev_i32_e32 v3, 31, v2
	s_and_saveexec_b64 s[40:41], s[8:9]
	s_xor_b64 s[40:41], exec, s[40:41]
	v_lshlrev_b64 v[0:1], 6, v[2:3]
	v_lshl_add_u64 v[0:1], v[104:105], 0, v[0:1]
	v_lshl_add_u64 v[0:1], v[0:1], 0, s[74:75]
	s_andn2_saveexec_b64 s[40:41], s[40:41]
	v_lshlrev_b64 v[0:1], 11, v[2:3]
	v_lshl_add_u64 v[0:1], s[46:47], 0, v[0:1]
	v_lshl_add_u64 v[0:1], v[106:107], 1, v[0:1]
	s_or_b64 exec, exec, s[40:41]
	s_add_i32 m0, s19, 0x6000
	v_add_u32_e32 v2, s36, v136
	global_load_lds_dwordx4 v[0:1], off
	v_ashrrev_i32_e32 v3, 31, v2
	s_and_saveexec_b64 s[40:41], s[12:13]
	s_xor_b64 s[40:41], exec, s[40:41]
	v_lshlrev_b64 v[0:1], 6, v[2:3]
	v_lshl_add_u64 v[0:1], v[108:109], 0, v[0:1]
	v_lshl_add_u64 v[0:1], v[0:1], 0, s[74:75]
	s_andn2_saveexec_b64 s[40:41], s[40:41]
	v_lshlrev_b64 v[0:1], 11, v[2:3]
	v_lshl_add_u64 v[0:1], s[46:47], 0, v[0:1]
	v_lshl_add_u64 v[0:1], v[110:111], 1, v[0:1]
	s_or_b64 exec, exec, s[40:41]
	s_add_i32 m0, s35, 0x6000
	s_ashr_i32 s37, s36, 31
	global_load_lds_dwordx4 v[0:1], off
	v_lshl_add_u64 v[0:1], s[36:37], 1, v[120:121]
	v_mov_b32_e32 v117, v113
	v_lshl_add_u64 v[0:1], v[0:1], 0, v[116:117]
	s_add_i32 m0, s19, 0x11000
	v_add_u32_e32 v48, 0, v124
	global_load_lds_dwordx4 v[0:1], off
	v_add_u32_e32 v49, 0, v125
	v_add_u32_e32 v50, 0, v126
	v_add_u32_e32 v51, 0, v127
	v_add_u32_e32 v52, 0, v128
	v_add_u32_e32 v53, 0, v129
	ds_read_b128 v[0:3], v48
	ds_read_b128 v[16:19], v48 offset:6144
	ds_read_b128 v[20:23], v49
	ds_read_b128 v[24:27], v49 offset:6144
	ds_read_b128 v[28:31], v50
	ds_read_b128 v[54:57], v50 offset:6144
	ds_read_b128 v[58:61], v51
	ds_read_b128 v[62:65], v51 offset:6144
	ds_read_b128 v[66:69], v52
	ds_read_b128 v[70:73], v52 offset:6144
	ds_read_b128 v[74:77], v53
	ds_read_b128 v[138:141], v53 offset:6144
	s_waitcnt lgkmcnt(0)
	v_mfma_f32_32x32x16_bf16 v[0:15], v[0:3], v[80:83], 0
	v_mfma_f32_32x32x16_bf16 v[0:15], v[20:23], v[84:87], v[0:15]
	v_mfma_f32_32x32x16_bf16 v[0:15], v[28:31], v[88:91], v[0:15]
	v_mfma_f32_32x32x16_bf16 v[0:15], v[58:61], v[92:95], v[0:15]
	v_mfma_f32_32x32x16_bf16 v[0:15], v[66:69], v[96:99], v[0:15]
	v_mfma_f32_32x32x16_bf16 v[32:47], v[16:19], v[80:83], 0
	v_mfma_f32_32x32x16_bf16 v[0:15], v[74:77], v[100:103], v[0:15]
	v_mfma_f32_32x32x16_bf16 v[32:47], v[24:27], v[84:87], v[32:47]
	s_nop 10
	v_max_f32_e32 v16, v1, v1
	v_max_f32_e32 v17, v0, v0
	v_max_f32_e32 v16, v17, v16
	v_max3_f32 v16, v16, v2, v3
	v_max3_f32 v16, v16, v4, v5
	v_max3_f32 v16, v16, v6, v7
	v_max3_f32 v16, v16, v8, v9
	v_mfma_f32_32x32x16_bf16 v[32:47], v[54:57], v[88:91], v[32:47]
	v_max3_f32 v16, v16, v10, v11
	v_max3_f32 v16, v16, v12, v13
	v_max3_f32 v16, v16, v14, v15
	v_mfma_f32_32x32x16_bf16 v[32:47], v[62:65], v[92:95], v[32:47]
	v_mfma_f32_32x32x16_bf16 v[32:47], v[70:73], v[96:99], v[32:47]
	v_mfma_f32_32x32x16_bf16 v[32:47], v[138:141], v[100:103], v[32:47]
	s_nop 11
	v_max3_f32 v16, v16, v32, v33
	v_max3_f32 v16, v16, v34, v35
	v_max3_f32 v16, v16, v36, v37
	v_max3_f32 v16, v16, v38, v39
	v_max3_f32 v16, v16, v40, v41
	v_max3_f32 v16, v16, v42, v43
	v_max3_f32 v16, v16, v44, v45
	v_max3_f32 v16, v16, v46, v47
	v_cmp_lt_f32_e32 vcc, s58, v16
	s_cbranch_vccz .LBB0_609
	v_mov_b32_e32 v17, v16
	v_mov_b32_e32 v18, v16
	s_nop 1
	v_permlane32_swap_b32_e32 v17, v18
	v_cndmask_b32_e64 v17, v17, v18, s[4:5]
	v_max3_f32 v16, v16, v17, 0
	v_pk_add_f32 v[0:1], v[0:1], v[16:17] op_sel_hi:[1,0] neg_lo:[0,1] neg_hi:[0,1]
	v_pk_add_f32 v[2:3], v[2:3], v[16:17] op_sel_hi:[1,0] neg_lo:[0,1] neg_hi:[0,1]
	v_pk_add_f32 v[4:5], v[4:5], v[16:17] op_sel_hi:[1,0] neg_lo:[0,1] neg_hi:[0,1]
	v_pk_add_f32 v[6:7], v[6:7], v[16:17] op_sel_hi:[1,0] neg_lo:[0,1] neg_hi:[0,1]
	v_pk_add_f32 v[8:9], v[8:9], v[16:17] op_sel_hi:[1,0] neg_lo:[0,1] neg_hi:[0,1]
	v_exp_f32_e64 v17, -v16
	v_add_f32_e32 v119, 0, v16
	v_sub_f32_e32 v47, v47, v16
	v_sub_f32_e32 v46, v46, v16
	v_pk_add_f32 v[10:11], v[10:11], v[16:17] op_sel_hi:[1,0] neg_lo:[0,1] neg_hi:[0,1]
	v_pk_add_f32 v[12:13], v[12:13], v[16:17] op_sel_hi:[1,0] neg_lo:[0,1] neg_hi:[0,1]
	v_pk_add_f32 v[14:15], v[14:15], v[16:17] op_sel_hi:[1,0] neg_lo:[0,1] neg_hi:[0,1]
	v_mul_f32_e32 v64, 0, v17
	v_sub_f32_e32 v45, v45, v16
	v_sub_f32_e32 v44, v44, v16
	v_sub_f32_e32 v43, v43, v16
	v_sub_f32_e32 v42, v42, v16
	v_sub_f32_e32 v41, v41, v16
	v_sub_f32_e32 v40, v40, v16
	v_sub_f32_e32 v39, v39, v16
	v_sub_f32_e32 v38, v38, v16
	v_sub_f32_e32 v37, v37, v16
	v_sub_f32_e32 v36, v36, v16
	v_sub_f32_e32 v35, v35, v16
	v_sub_f32_e32 v34, v34, v16
	v_sub_f32_e32 v33, v33, v16
	v_sub_f32_e32 v32, v32, v16
	s_branch .LBB0_610

; #define AT_LOADV(t, sl) do { const int m0_ = AT_M0(t); LAS unsigned char* vd_ = lds + AT_V0 + (sl) * AT_VB; \
;         _Pragma("unroll") for (int i = 0; i < NVL; ++i) { const int piece = wave + 8 * i; const int row = 8 * piece + (lane >> 3), c16 = (lane & 7) ^ ((row >> 1) & 7); \
;             AT_DMA(vbase + (size_t)row * MT + m0_ + 8 * c16, vd_ + 1024 * piece); } } while (0)
; template <int DQ, int DV, bool WINDOW, bool GQA = false> ...
;     ...
;             { const bool deep = 2 < nt; if (deep) { AT_LOADK(2, k2_); AT_LOADV(2, 2); }
;               AT_QKS(0, k0_);
.LBB0_636:
	s_and_b64 vcc, exec, s[36:37]
	s_cbranch_vccz .LBB0_577
	s_or_b32 s40, s26, 0x80
	s_nop 5
	v_add_u32_e32 v2, s40, v135
	v_ashrrev_i32_e32 v3, 31, v2
	s_and_saveexec_b64 s[36:37], s[8:9]
	s_xor_b64 s[36:37], exec, s[36:37]
	v_lshlrev_b64 v[0:1], 6, v[2:3]
	v_lshl_add_u64 v[0:1], v[104:105], 0, v[0:1]
	v_lshl_add_u64 v[0:1], v[0:1], 0, s[74:75]
	s_andn2_saveexec_b64 s[36:37], s[36:37]
	v_lshlrev_b64 v[0:1], 11, v[2:3]
	v_lshl_add_u64 v[0:1], s[46:47], 0, v[0:1]
	v_lshl_add_u64 v[0:1], v[106:107], 1, v[0:1]
	s_or_b64 exec, exec, s[36:37]
	s_add_i32 m0, s19, 0x6000
	v_add_u32_e32 v2, s40, v136
	global_load_lds_dwordx4 v[0:1], off
	v_ashrrev_i32_e32 v3, 31, v2
	s_and_saveexec_b64 s[36:37], s[12:13]
	s_xor_b64 s[36:37], exec, s[36:37]
	v_lshlrev_b64 v[0:1], 6, v[2:3]
	v_lshl_add_u64 v[0:1], v[108:109], 0, v[0:1]
	v_lshl_add_u64 v[0:1], v[0:1], 0, s[74:75]
	s_andn2_saveexec_b64 s[36:37], s[36:37]
	v_lshlrev_b64 v[0:1], 11, v[2:3]
	v_lshl_add_u64 v[0:1], s[46:47], 0, v[0:1]
	v_lshl_add_u64 v[0:1], v[110:111], 1, v[0:1]
	s_or_b64 exec, exec, s[36:37]
	v_mov_b32_e32 v117, v113
	v_lshl_add_u64 v[120:121], v[120:121], 0, v[116:117]
	s_add_i32 m0, s35, 0x6000
	v_lshl_add_u64 v[48:49], s[26:27], 1, v[120:121]
	s_mov_b64 s[36:37], 0x100
	global_load_lds_dwordx4 v[0:1], off
	v_lshl_add_u64 v[0:1], v[48:49], 0, s[36:37]
	s_add_i32 m0, s30, 0x8000
	v_add_u32_e32 v50, 0, v124
	global_load_lds_dwordx4 v[0:1], off
	v_add_u32_e32 v51, 0, v125
	v_add_u32_e32 v52, 0, v126
	v_add_u32_e32 v53, 0, v127
	v_add_u32_e32 v54, 0, v128
	v_add_u32_e32 v55, 0, v129
	ds_read_b128 v[0:3], v50
	ds_read_b128 v[16:19], v50 offset:6144
	ds_read_b128 v[20:23], v51
	ds_read_b128 v[24:27], v51 offset:6144
	ds_read_b128 v[28:31], v52
	ds_read_b128 v[56:59], v52 offset:6144
	ds_read_b128 v[60:63], v53
	ds_read_b128 v[64:67], v53 offset:6144
	ds_read_b128 v[68:71], v54
	ds_read_b128 v[72:75], v54 offset:6144
	ds_read_b128 v[76:79], v55
	ds_read_b128 v[138:141], v55 offset:6144
	s_waitcnt lgkmcnt(0)
	v_mfma_f32_32x32x16_bf16 v[0:15], v[0:3], v[80:83], 0
	v_mfma_f32_32x32x16_bf16 v[32:47], v[16:19], v[80:83], 0
	v_mfma_f32_32x32x16_bf16 v[0:15], v[20:23], v[84:87], v[0:15]
	v_mfma_f32_32x32x16_bf16 v[32:47], v[24:27], v[84:87], v[32:47]
	v_mfma_f32_32x32x16_bf16 v[0:15], v[28:31], v[88:91], v[0:15]
	v_mfma_f32_32x32x16_bf16 v[32:47], v[56:59], v[88:91], v[32:47]
	v_mfma_f32_32x32x16_bf16 v[0:15], v[60:63], v[92:95], v[0:15]
	v_mfma_f32_32x32x16_bf16 v[32:47], v[64:67], v[92:95], v[32:47]
	v_mfma_f32_32x32x16_bf16 v[0:15], v[68:71], v[96:99], v[0:15]
	v_mfma_f32_32x32x16_bf16 v[32:47], v[72:75], v[96:99], v[32:47]
	v_mfma_f32_32x32x16_bf16 v[0:15], v[76:79], v[100:103], v[0:15]
	v_mfma_f32_32x32x16_bf16 v[32:47], v[138:141], v[100:103], v[32:47]
	s_nop 10
	v_max_f32_e32 v16, v1, v1
	v_max_f32_e32 v17, v0, v0
	v_max_f32_e32 v16, v17, v16
	v_max3_f32 v16, v16, v2, v3
	v_max3_f32 v16, v16, v4, v5
	v_max3_f32 v16, v16, v6, v7
	v_max3_f32 v16, v16, v8, v9
	v_max3_f32 v16, v16, v10, v11
	v_max3_f32 v16, v16, v12, v13
	v_max3_f32 v16, v16, v14, v15
	v_max3_f32 v16, v16, v32, v33
	v_max3_f32 v16, v16, v34, v35
	v_max3_f32 v16, v16, v36, v37
	v_max3_f32 v16, v16, v38, v39
	v_max3_f32 v16, v16, v40, v41
	v_max3_f32 v16, v16, v42, v43
	v_max3_f32 v16, v16, v44, v45
	v_max3_f32 v16, v16, v46, v47
	v_cmp_lt_f32_e32 vcc, s58, v16
	s_cbranch_vccz .LBB0_647
	v_mov_b32_e32 v17, v16
	v_mov_b32_e32 v18, v16
	s_nop 1
	v_permlane32_swap_b32_e32 v17, v18
	v_cndmask_b32_e64 v17, v17, v18, s[4:5]
	v_max3_f32 v16, v16, v17, 0
	v_pk_add_f32 v[0:1], v[0:1], v[16:17] op_sel_hi:[1,0] neg_lo:[0,1] neg_hi:[0,1]
	v_pk_add_f32 v[32:33], v[32:33], v[16:17] op_sel_hi:[1,0] neg_lo:[0,1] neg_hi:[0,1]
	v_pk_add_f32 v[2:3], v[2:3], v[16:17] op_sel_hi:[1,0] neg_lo:[0,1] neg_hi:[0,1]
	v_pk_add_f32 v[34:35], v[34:35], v[16:17] op_sel_hi:[1,0] neg_lo:[0,1] neg_hi:[0,1]
	v_pk_add_f32 v[4:5], v[4:5], v[16:17] op_sel_hi:[1,0] neg_lo:[0,1] neg_hi:[0,1]
	v_pk_add_f32 v[36:37], v[36:37], v[16:17] op_sel_hi:[1,0] neg_lo:[0,1] neg_hi:[0,1]
	v_pk_add_f32 v[6:7], v[6:7], v[16:17] op_sel_hi:[1,0] neg_lo:[0,1] neg_hi:[0,1]
	v_pk_add_f32 v[38:39], v[38:39], v[16:17] op_sel_hi:[1,0] neg_lo:[0,1] neg_hi:[0,1]
	v_pk_add_f32 v[8:9], v[8:9], v[16:17] op_sel_hi:[1,0] neg_lo:[0,1] neg_hi:[0,1]
	v_pk_add_f32 v[40:41], v[40:41], v[16:17] op_sel_hi:[1,0] neg_lo:[0,1] neg_hi:[0,1]
	v_pk_add_f32 v[10:11], v[10:11], v[16:17] op_sel_hi:[1,0] neg_lo:[0,1] neg_hi:[0,1]
	v_pk_add_f32 v[42:43], v[42:43], v[16:17] op_sel_hi:[1,0] neg_lo:[0,1] neg_hi:[0,1]
	v_pk_add_f32 v[12:13], v[12:13], v[16:17] op_sel_hi:[1,0] neg_lo:[0,1] neg_hi:[0,1]
	v_exp_f32_e64 v17, -v16
	v_add_f32_e32 v117, 0, v16
	v_pk_add_f32 v[44:45], v[44:45], v[16:17] op_sel_hi:[1,0] neg_lo:[0,1] neg_hi:[0,1]
	v_pk_add_f32 v[14:15], v[14:15], v[16:17] op_sel_hi:[1,0] neg_lo:[0,1] neg_hi:[0,1]
	v_pk_add_f32 v[46:47], v[46:47], v[16:17] op_sel_hi:[1,0] neg_lo:[0,1] neg_hi:[0,1]
	v_mul_f32_e32 v64, 0, v17
	s_branch .LBB0_648

; #define AT_BAR() do { asm volatile("s_waitcnt lgkmcnt(0)" ::: "memory"); __builtin_amdgcn_s_barrier(); asm volatile("" ::: "memory"); } while (0)
; #define AT_LOADV(t, sl) do { const int m0_ = AT_M0(t); LAS unsigned char* vd_ = lds + AT_V0 + (sl) * AT_VB; \
;         _Pragma("unroll") for (int i = 0; i < NVL; ++i) { const int piece = wave + 8 * i; const int row = 8 * piece + (lane >> 3), c16 = (lane & 7) ^ ((row >> 1) & 7); \
;             AT_DMA(vbase + (size_t)row * MT + m0_ + 8 * c16, vd_ + 1024 * piece); } } while (0)
; #define AT_VMW(n) asm volatile("s_waitcnt vmcnt(%0)" :: "n"(n) : "memory")
; template <int DQ, int DV, bool WINDOW, bool GQA = false> ...
;     ...
;         else { int qb64, kvh; if (!isctx) { qb64 = u & 63; kvh = (u >> 6) & 3; b = u >> 8; } else { const int v = u - nunits_lat; qb64 = v & 3; kvh = (v >> 2) & 3; b = v >> 4; } hq = kvh * 4 + (wave >> 1); qrow0 = qb64 * 64 + (wave & 1) * 32; }
;         const int ublk0 = GQA ? (qrow0 & ~63) : (qrow0 & ~255), ublen = GQA ? 64 : 256;
;         const int mqw = (isctx ? TL + b * CTXL : b * SEQ) + qrow0;
;         int lt0 = 0, nlt = 0;
;         if (!isctx) { if (WINDOW) { const int lo = (ublk0 - 128) < 0 ? 0 : (ublk0 - 128); const int hi = (ublk0 + ublen + 128) > SEQ ? SEQ : (ublk0 + ublen + 128); lt0 = lo >> 6; nlt = (hi - lo) >> 6; } else { lt0 = 0; nlt = 64; } }
;         const int nt = 4 + nlt;
;         bf16x8 qf[NKS];
;         { const bf16* qp = Q + (size_t)(mqw + r32) * ldq + hq * DQ + 8 * hh;
; #pragma unroll
;           for (int ks = 0; ks < NKS; ++ks) qf[ks] = *(const bf16x8*)(qp + 16 * ks); }
;         float m_run, l_run;
;         m_run = 0.f; l_run = (sink && hh == 0) ? __builtin_amdgcn_exp2f(sink[hq] * LOG2E) : 0.f;
;     ...
;         AT_LOADK(0, 0); AT_LOADV(0, 0); AT_LOADK(1, 1); AT_LOADV(1, 1); AT_VMW(NKL + NVL); AT_BAR();
;         if (grp == 0) {
.LBB0_892:
	s_lshl_b32 s26, s34, 2
	s_and_b32 s26, s26, 12
	s_lshl_b32 s42, s28, 6
	s_lshl_b32 s41, s29, 8
	s_add_i32 s34, s26, s3
	s_or_b32 s43, s42, s19
	s_add_i32 s28, s41, 0x8000
	s_lshl_b32 s46, s29, 12
	s_and_b64 s[26:27], exec, s[6:7]
	s_cselect_b32 s26, s28, s46
	s_add_i32 s26, s26, s43
	v_or_b32_e32 v0, s26, v89
	v_ashrrev_i32_e32 v1, 31, v0
	v_lshlrev_b64 v[94:95], 11, v[0:1]
	s_lshl_b32 s26, s34, 6
	v_lshl_add_u64 v[0:1], s[12:13], 0, v[94:95]
	s_ashr_i32 s27, s26, 31
	v_lshl_add_u64 v[0:1], s[26:27], 1, v[0:1]
	v_lshl_add_u64 v[0:1], v[0:1], 0, v[112:113]
	global_load_dwordx4 v[64:67], v[0:1], off
	global_load_dwordx4 v[68:71], v[0:1], off offset:32
	global_load_dwordx4 v[72:75], v[0:1], off offset:64
	global_load_dwordx4 v[76:79], v[0:1], off offset:96
	v_mov_b32_e32 v131, 0
	s_and_saveexec_b64 s[36:37], s[14:15]
	s_cbranch_execz .LBB0_894
	s_ashr_i32 s35, s34, 31
	s_lshl_b64 s[48:49], s[34:35], 2
	s_add_u32 s48, s8, s48
	s_addc_u32 s49, s9, s49
	global_load_dword v176, v113, s[48:49]
.LBB0_894:
	s_or_b64 exec, exec, s[36:37]
	v_sub_u32_e64 v0, s42, v230 clamp
	s_min_u32 s29, s42, 0xf40
	v_readfirstlane_b32 s35, v0
	s_sub_i32 s29, s29, s35
	s_addk_i32 s29, 0xc0
	s_ashr_i32 s29, s29, 6
	s_lshr_b32 s36, s35, 6
	s_add_i32 s29, s29, 4
	s_and_b64 s[6:7], exec, s[6:7]
	s_cselect_b32 s38, 4, s29
	s_cselect_b32 s40, 0, s36
	s_ashr_i32 s6, s34, 2
	s_ashr_i32 s7, s6, 31
	s_lshl_b32 s29, s34, 4
	s_lshl_b64 s[6:7], s[6:7], 7
	s_andn2_b32 s29, s29, 63
	v_add_u32_e32 v0, s28, v111
	s_add_u32 s6, s1, s6
	v_ashrrev_i32_e32 v1, 31, v0
	s_addc_u32 s7, s2, s7
	v_lshlrev_b64 v[0:1], 9, v[0:1]
	v_lshl_add_u64 v[0:1], s[6:7], 0, v[0:1]
	v_lshlrev_b32_e32 v96, 1, v90
	v_mov_b32_e32 v97, v113
	s_mov_b32 m0, s30
	v_lshl_add_u64 v[0:1], v[0:1], 0, v[96:97]
	v_mad_i64_i32 v[98:99], s[34:35], s29, v231, v[92:93]
	s_ashr_i32 s29, s28, 31
	global_load_lds_dwordx4 v[0:1], off
	v_lshl_add_u64 v[0:1], s[28:29], 1, v[98:99]
	v_lshl_add_u64 v[0:1], v[0:1], 0, v[96:97]
	s_mov_b32 m0, s31
	s_add_i32 s34, s41, 0x8040
	global_load_lds_dwordx4 v[0:1], off
	v_add_u32_e32 v0, s34, v111
	v_ashrrev_i32_e32 v1, 31, v0
	v_lshlrev_b64 v[0:1], 9, v[0:1]
	v_lshl_add_u64 v[0:1], s[6:7], 0, v[0:1]
	v_lshl_add_u64 v[0:1], v[0:1], 0, v[96:97]
	s_add_i32 m0, s30, 0x3000
	s_ashr_i32 s35, s34, 31
	global_load_lds_dwordx4 v[0:1], off
	v_lshl_add_u64 v[0:1], s[34:35], 1, v[98:99]
	v_lshl_add_u64 v[0:1], v[0:1], 0, v[96:97]
	s_add_i32 m0, s30, 0xd000
	s_mov_b64 s[34:35], -1
	global_load_lds_dwordx4 v[0:1], off
	s_waitcnt vmcnt(2)
	s_waitcnt lgkmcnt(0)
	s_barrier
	s_and_saveexec_b64 s[36:37], s[14:15]
	v_mul_f32_e32 v176, 0x3fb8aa3b, v176
	v_exp_f32_e32 v131, v176
	s_or_b64 exec, exec, s[36:37]
	s_and_b64 vcc, exec, s[16:17]
	s_cbranch_vccz .LBB0_937
	s_cmp_lt_i32 s38, 3
	s_cselect_b64 s[34:35], -1, 0
	s_and_b64 vcc, exec, s[34:35]
	s_cbranch_vccnz .LBB0_897
	s_add_i32 s36, s41, 0x8080
	v_add_u32_e32 v0, s36, v111
	v_ashrrev_i32_e32 v1, 31, v0
	v_lshlrev_b64 v[0:1], 9, v[0:1]
	v_lshl_add_u64 v[0:1], s[6:7], 0, v[0:1]
	v_mov_b32_e32 v97, v113
	v_lshl_add_u64 v[0:1], v[0:1], 0, v[96:97]
	s_add_i32 m0, s30, 0x6000
	s_ashr_i32 s37, s36, 31
	global_load_lds_dwordx4 v[0:1], off
	v_lshl_add_u64 v[0:1], s[36:37], 1, v[98:99]
	v_lshl_add_u64 v[0:1], v[0:1], 0, v[96:97]
	s_add_i32 m0, s30, 0x11000
	s_nop 0
	global_load_lds_dwordx4 v[0:1], off
.LBB0_897:
	v_add_u32_e32 v134, 0, v91
	v_add_u32_e32 v135, 0, v104
	v_add_u32_e32 v136, 0, v105
	v_add_u32_e32 v137, 0, v106
	ds_read_b128 v[0:3], v134
	ds_read_b128 v[4:7], v134 offset:4096
	ds_read_b128 v[8:11], v135
	ds_read_b128 v[12:15], v135 offset:4096
	ds_read_b128 v[16:19], v136
	ds_read_b128 v[20:23], v136 offset:4096
	ds_read_b128 v[24:27], v137
	ds_read_b128 v[28:31], v137 offset:4096
	s_waitcnt lgkmcnt(0)
	v_mfma_f32_32x32x16_bf16 v[48:63], v[0:3], v[64:67], 0
	v_mfma_f32_32x32x16_bf16 v[48:63], v[8:11], v[68:71], v[48:63]
	v_mfma_f32_32x32x16_bf16 v[48:63], v[16:19], v[72:75], v[48:63]
	v_mfma_f32_32x32x16_bf16 v[32:47], v[4:7], v[64:67], 0
	v_mfma_f32_32x32x16_bf16 v[48:63], v[24:27], v[76:79], v[48:63]
	v_mfma_f32_32x32x16_bf16 v[32:47], v[12:15], v[68:71], v[32:47]
	s_nop 10
	v_max_f32_e32 v0, v49, v49
	v_max_f32_e32 v1, v48, v48
	v_max_f32_e32 v0, v1, v0
	v_max3_f32 v0, v0, v50, v51
	v_max3_f32 v0, v0, v52, v53
	v_max3_f32 v0, v0, v54, v55
	v_max3_f32 v0, v0, v56, v57
	v_mfma_f32_32x32x16_bf16 v[32:47], v[20:23], v[72:75], v[32:47]
	v_max3_f32 v0, v0, v58, v59
	v_max3_f32 v0, v0, v60, v61
	v_max3_f32 v0, v0, v62, v63
	v_mfma_f32_32x32x16_bf16 v[32:47], v[28:31], v[76:79], v[32:47]
	s_nop 11
	v_max3_f32 v0, v0, v32, v33
	v_max3_f32 v0, v0, v34, v35
	v_max3_f32 v0, v0, v36, v37
	v_max3_f32 v0, v0, v38, v39
	v_max3_f32 v0, v0, v40, v41
	v_max3_f32 v0, v0, v42, v43
	v_max3_f32 v0, v0, v44, v45
	v_max3_f32 v0, v0, v46, v47
	v_cmp_lt_f32_e32 vcc, s58, v0
	s_cbranch_vccz .LBB0_962
	v_mov_b32_e32 v1, v0
	v_mov_b32_e32 v2, v0
	s_nop 1
	v_permlane32_swap_b32_e32 v1, v2
	v_cndmask_b32_e64 v1, v1, v2, s[4:5]
	v_max3_f32 v100, v0, v1, 0
	v_exp_f32_e64 v97, -v100
	v_add_f32_e32 v132, 0, v100
	v_pk_add_f32 v[48:49], v[48:49], v[100:101] op_sel_hi:[1,0] neg_lo:[0,1] neg_hi:[0,1]
	v_pk_add_f32 v[50:51], v[50:51], v[100:101] op_sel_hi:[1,0] neg_lo:[0,1] neg_hi:[0,1]
	v_mul_f32_e32 v0, 0, v97
	v_pk_add_f32 v[52:53], v[52:53], v[100:101] op_sel_hi:[1,0] neg_lo:[0,1] neg_hi:[0,1]
	v_pk_add_f32 v[54:55], v[54:55], v[100:101] op_sel_hi:[1,0] neg_lo:[0,1] neg_hi:[0,1]
	v_pk_add_f32 v[56:57], v[56:57], v[100:101] op_sel_hi:[1,0] neg_lo:[0,1] neg_hi:[0,1]
	v_pk_add_f32 v[58:59], v[58:59], v[100:101] op_sel_hi:[1,0] neg_lo:[0,1] neg_hi:[0,1]
	v_pk_add_f32 v[60:61], v[60:61], v[100:101] op_sel_hi:[1,0] neg_lo:[0,1] neg_hi:[0,1]
	v_pk_add_f32 v[62:63], v[62:63], v[100:101] op_sel_hi:[1,0] neg_lo:[0,1] neg_hi:[0,1]
	v_mov_b32_e32 v1, v0
	v_mov_b32_e32 v2, v0
	v_mov_b32_e32 v3, v0
	v_mov_b32_e32 v4, v0
	v_mov_b32_e32 v5, v0
	v_mov_b32_e32 v6, v0
	v_mov_b32_e32 v7, v0
	v_mov_b32_e32 v8, v0
	v_mov_b32_e32 v9, v0
	v_mov_b32_e32 v10, v0
	v_mov_b32_e32 v11, v0
	v_mov_b32_e32 v12, v0
	v_mov_b32_e32 v13, v0
	v_mov_b32_e32 v14, v0
	v_mov_b32_e32 v15, v0
	v_mov_b32_e32 v16, v0
	v_mov_b32_e32 v17, v0
	v_mov_b32_e32 v18, v0
	v_mov_b32_e32 v19, v0
	v_mov_b32_e32 v20, v0
	v_mov_b32_e32 v21, v0
	v_mov_b32_e32 v22, v0
	v_mov_b32_e32 v23, v0
	v_mov_b32_e32 v24, v0
	v_mov_b32_e32 v25, v0
	v_mov_b32_e32 v26, v0
	v_mov_b32_e32 v27, v0
	v_mov_b32_e32 v28, v0
	v_mov_b32_e32 v29, v0
	v_mov_b32_e32 v30, v0
	v_mov_b32_e32 v31, v0
	v_sub_f32_e32 v47, v47, v100
	v_sub_f32_e32 v46, v46, v100
	v_sub_f32_e32 v45, v45, v100
	v_sub_f32_e32 v44, v44, v100
	v_sub_f32_e32 v43, v43, v100
	v_sub_f32_e32 v42, v42, v100
	v_sub_f32_e32 v41, v41, v100
	v_sub_f32_e32 v40, v40, v100
	v_sub_f32_e32 v39, v39, v100
	v_sub_f32_e32 v38, v38, v100
	v_sub_f32_e32 v37, v37, v100
	v_sub_f32_e32 v36, v36, v100
	v_sub_f32_e32 v35, v35, v100
	v_sub_f32_e32 v34, v34, v100
	v_sub_f32_e32 v33, v33, v100
	v_sub_f32_e32 v32, v32, v100
	v_mul_f32_e32 v97, v131, v97
	s_mov_b64 s[36:37], -1
	s_and_b64 vcc, exec, s[34:35]
	s_cbranch_vccz .LBB0_900

; template <int DQ, int DV, bool WINDOW, bool GQA = false> ...
;     ...
;         bf16x8 qf[NKS];
;         { const bf16* qp = Q + (size_t)(mqw + r32) * ldq + hq * DQ + 8 * hh;
; #pragma unroll
;           for (int ks = 0; ks < NKS; ++ks) qf[ks] = *(const bf16x8*)(qp + 16 * ks); }
;         float m_run, l_run;
;         m_run = 0.f; l_run = (sink && hh == 0) ? __builtin_amdgcn_exp2f(sink[hq] * LOG2E) : 0.f;
;         f32x16 o[NV];
; #pragma unroll
;         for (int v = 0; v < NV; ++v)
; #pragma unroll
;             for (int i = 0; i < 16; ++i) o[v][i] = 0.f;
;         const bf16* kbase = K1 + (size_t)(hq >> kshift) * 64;
;         const bf16* vbase = Vt + (size_t)((hq >> vshift) * DV) * MT;
;         bf16x8 pf[2]; f32x16 s1k; bool pact = true;
; #pragma unroll
;         for (int i = 0; i < 16; ++i) s1k[i] = 0.f;
.LBB0_1468:
	s_lshl_b32 s13, s26, 8
	s_and_b32 s38, s15, 15
	s_add_i32 s14, s13, 0x8000
	s_lshl_b32 s12, s26, 12
	s_and_b64 s[16:17], exec, s[16:17]
	s_cselect_b32 s16, s14, s12
	s_add_i32 s16, s16, s27
	v_add_u32_e32 v138, s16, v155
	v_ashrrev_i32_e32 v139, 31, v138
	v_lshlrev_b64 v[0:1], 11, v[138:139]
	s_lshl_b32 s15, s15, 6
	v_lshl_add_u64 v[0:1], s[8:9], 0, v[0:1]
	s_lshl_b32 s44, s38, 7
	s_and_b32 s15, s15, 0x380
	v_lshl_add_u64 v[0:1], v[0:1], 0, s[44:45]
	v_lshlrev_b32_e32 v140, 1, v130
	v_mov_b32_e32 v141, v113
	s_add_u32 s16, s3, s44
	v_lshl_add_u64 v[0:1], v[0:1], 0, v[140:141]
	s_addc_u32 s17, s19, 0
	s_mul_i32 s15, s15, 0x11000
	global_load_dwordx4 v[114:117], v[0:1], off
	global_load_dwordx4 v[118:121], v[0:1], off offset:32
	global_load_dwordx4 v[122:125], v[0:1], off offset:64
	global_load_dwordx4 v[126:129], v[0:1], off offset:96
	s_add_u32 s41, s30, s15
	v_add_u32_e32 v0, s14, v156
	s_addc_u32 s42, s31, 0
	v_ashrrev_i32_e32 v1, 31, v0
	s_ashr_i32 s15, s14, 31
	v_lshlrev_b64 v[0:1], 11, v[0:1]
	s_lshl_b64 s[26:27], s[14:15], 1
	v_lshl_add_u64 v[0:1], s[16:17], 0, v[0:1]
	s_add_u32 s26, s41, s26
	s_mov_b32 m0, s36
	v_lshl_add_u64 v[0:1], v[0:1], 0, v[112:113]
	s_addc_u32 s27, s42, s27
	global_load_lds_dwordx4 v[0:1], off
	v_lshl_add_u64 v[0:1], s[26:27], 0, v[132:133]
	v_lshl_add_u64 v[142:143], v[0:1], 0, v[112:113]
	v_lshl_add_u64 v[0:1], s[26:27], 0, v[134:135]
	v_mov_b32_e32 v137, v113
	s_add_i32 s26, s13, 0x8040
	s_add_i32 m0, s36, 0x9000
	v_lshl_add_u64 v[144:145], v[0:1], 0, v[136:137]
	s_add_i32 s15, s37, 0
	v_add_u32_e32 v0, s26, v156
	global_load_lds_dwordx4 v[142:143], off
	s_add_i32 m0, s15, 0x9000
	v_ashrrev_i32_e32 v1, 31, v0
	s_ashr_i32 s27, s26, 31
	global_load_lds_dwordx4 v[144:145], off
	v_lshlrev_b64 v[0:1], 11, v[0:1]
	s_add_i32 m0, s36, 0x3000
	s_lshl_b64 s[26:27], s[26:27], 1
	v_lshl_add_u64 v[0:1], s[16:17], 0, v[0:1]
	s_add_u32 s26, s41, s26
	v_lshl_add_u64 v[0:1], v[0:1], 0, v[112:113]
	s_addc_u32 s27, s42, s27
	global_load_lds_dwordx4 v[0:1], off
	v_lshl_add_u64 v[0:1], s[26:27], 0, v[132:133]
	v_lshl_add_u64 v[0:1], v[0:1], 0, v[112:113]
	s_add_i32 m0, s36, 0xd000
	s_and_b64 vcc, exec, s[10:11]
	global_load_lds_dwordx4 v[0:1], off
	v_lshl_add_u64 v[0:1], s[26:27], 0, v[134:135]
	v_lshl_add_u64 v[0:1], v[0:1], 0, v[136:137]
	s_add_i32 m0, s15, 0xd000
	s_mov_b64 s[26:27], -1
	global_load_lds_dwordx4 v[0:1], off
	s_waitcnt vmcnt(3)
	s_waitcnt lgkmcnt(0)
	s_barrier
	v_add_u32_e32 v161, 0, v131
	v_add_u32_e32 v160, 0, v148
	v_add_u32_e32 v159, 0, v149
	v_add_u32_e32 v141, 0, v150
	s_cbranch_vccz .LBB0_1490
	s_add_i32 s26, s13, 0x8080
	v_add_u32_e32 v0, s26, v156
	v_ashrrev_i32_e32 v1, 31, v0
	s_ashr_i32 s27, s26, 31
	v_lshlrev_b64 v[0:1], 11, v[0:1]
	s_add_i32 m0, s36, 0x6000
	s_lshl_b64 s[26:27], s[26:27], 1
	v_lshl_add_u64 v[0:1], s[16:17], 0, v[0:1]
	s_add_u32 s26, s41, s26
	v_lshl_add_u64 v[0:1], v[0:1], 0, v[112:113]
	s_addc_u32 s27, s42, s27
	global_load_lds_dwordx4 v[0:1], off
	v_lshl_add_u64 v[0:1], s[26:27], 0, v[132:133]
	s_add_i32 s13, 0, 0x11000
	v_lshl_add_u64 v[0:1], v[0:1], 0, v[112:113]
	s_add_i32 m0, s13, s33
	s_nop 0
	global_load_lds_dwordx4 v[0:1], off
	v_lshl_add_u64 v[0:1], s[26:27], 0, v[134:135]
	v_lshl_add_u64 v[0:1], v[0:1], 0, v[136:137]
	s_add_i32 m0, s13, s37
	s_nop 0
	global_load_lds_dwordx4 v[0:1], off
	ds_read_b128 v[0:3], v161
	ds_read_b128 v[16:19], v161 offset:4096
	ds_read_b128 v[20:23], v160
	ds_read_b128 v[24:27], v160 offset:4096
	ds_read_b128 v[28:31], v159
	ds_read_b128 v[32:35], v159 offset:4096
	ds_read_b128 v[36:39], v141
	ds_read_b128 v[40:43], v141 offset:4096
	s_waitcnt lgkmcnt(0)
	v_mfma_f32_32x32x16_bf16 v[0:15], v[0:3], v[114:117], 0
	v_mfma_f32_32x32x16_bf16 v[0:15], v[20:23], v[118:121], v[0:15]
	v_mfma_f32_32x32x16_bf16 v[0:15], v[28:31], v[122:125], v[0:15]
	v_mfma_f32_32x32x16_bf16 v[64:79], v[16:19], v[114:117], 0
	v_mfma_f32_32x32x16_bf16 v[0:15], v[36:39], v[126:129], v[0:15]
	v_mfma_f32_32x32x16_bf16 v[64:79], v[24:27], v[118:121], v[64:79]
	s_nop 10
	v_max_f32_e32 v16, v1, v1
	v_max_f32_e32 v17, v0, v0
	v_max_f32_e32 v16, v17, v16
	v_max3_f32 v16, v16, v2, v3
	v_max3_f32 v16, v16, v4, v5
	v_max3_f32 v16, v16, v6, v7
	v_max3_f32 v16, v16, v8, v9
	v_mfma_f32_32x32x16_bf16 v[64:79], v[32:35], v[122:125], v[64:79]
	v_max3_f32 v16, v16, v10, v11
	v_max3_f32 v16, v16, v12, v13
	v_max3_f32 v16, v16, v14, v15
	v_mfma_f32_32x32x16_bf16 v[64:79], v[40:43], v[126:129], v[64:79]
	s_nop 11
	v_max3_f32 v16, v16, v64, v65
	v_max3_f32 v16, v16, v66, v67
	v_max3_f32 v16, v16, v68, v69
	v_max3_f32 v16, v16, v70, v71
	v_max3_f32 v16, v16, v72, v73
	v_max3_f32 v16, v16, v74, v75
	v_max3_f32 v16, v16, v76, v77
	v_max3_f32 v16, v16, v78, v79
	v_cmp_lt_f32_e32 vcc, s58, v16
	s_cbranch_vccz .LBB0_1471
	v_mov_b32_e32 v17, v16
	v_mov_b32_e32 v18, v16
	s_nop 1
	v_permlane32_swap_b32_e32 v17, v18
	v_cndmask_b32_e64 v17, v17, v18, s[4:5]
	v_max3_f32 v16, v16, v17, 0
	v_pk_add_f32 v[0:1], v[0:1], v[16:17] op_sel_hi:[1,0] neg_lo:[0,1] neg_hi:[0,1]
	v_pk_add_f32 v[64:65], v[64:65], v[16:17] op_sel_hi:[1,0] neg_lo:[0,1] neg_hi:[0,1]
	v_pk_add_f32 v[2:3], v[2:3], v[16:17] op_sel_hi:[1,0] neg_lo:[0,1] neg_hi:[0,1]
	v_pk_add_f32 v[66:67], v[66:67], v[16:17] op_sel_hi:[1,0] neg_lo:[0,1] neg_hi:[0,1]
	v_pk_add_f32 v[4:5], v[4:5], v[16:17] op_sel_hi:[1,0] neg_lo:[0,1] neg_hi:[0,1]
	v_pk_add_f32 v[68:69], v[68:69], v[16:17] op_sel_hi:[1,0] neg_lo:[0,1] neg_hi:[0,1]
	v_pk_add_f32 v[6:7], v[6:7], v[16:17] op_sel_hi:[1,0] neg_lo:[0,1] neg_hi:[0,1]
	v_pk_add_f32 v[70:71], v[70:71], v[16:17] op_sel_hi:[1,0] neg_lo:[0,1] neg_hi:[0,1]
	v_pk_add_f32 v[8:9], v[8:9], v[16:17] op_sel_hi:[1,0] neg_lo:[0,1] neg_hi:[0,1]
	v_pk_add_f32 v[72:73], v[72:73], v[16:17] op_sel_hi:[1,0] neg_lo:[0,1] neg_hi:[0,1]
	v_pk_add_f32 v[10:11], v[10:11], v[16:17] op_sel_hi:[1,0] neg_lo:[0,1] neg_hi:[0,1]
	v_pk_add_f32 v[74:75], v[74:75], v[16:17] op_sel_hi:[1,0] neg_lo:[0,1] neg_hi:[0,1]
	v_pk_add_f32 v[12:13], v[12:13], v[16:17] op_sel_hi:[1,0] neg_lo:[0,1] neg_hi:[0,1]
	v_exp_f32_e64 v17, -v16
	v_add_f32_e32 v164, 0, v16
	v_pk_add_f32 v[76:77], v[76:77], v[16:17] op_sel_hi:[1,0] neg_lo:[0,1] neg_hi:[0,1]
	v_pk_add_f32 v[14:15], v[14:15], v[16:17] op_sel_hi:[1,0] neg_lo:[0,1] neg_hi:[0,1]
	v_pk_add_f32 v[78:79], v[78:79], v[16:17] op_sel_hi:[1,0] neg_lo:[0,1] neg_hi:[0,1]
	v_mul_f32_e32 v96, 0, v17
	s_branch .LBB0_1472

; #define AT_LOADV(t, sl) do { const int m0_ = AT_M0(t); LAS unsigned char* vd_ = lds + AT_V0 + (sl) * AT_VB; \
;         _Pragma("unroll") for (int i = 0; i < NVL; ++i) { const int piece = wave + 8 * i; const int row = 8 * piece + (lane >> 3), c16 = (lane & 7) ^ ((row >> 1) & 7); \
;             AT_DMA(vbase + (size_t)row * MT + m0_ + 8 * c16, vd_ + 1024 * piece); } } while (0)
; template <int DQ, int DV, bool WINDOW, bool GQA = false> ...
;     ...
;             { const bool deep = 2 < nt; if (deep) { AT_LOADK(2, k2_); AT_LOADV(2, 2); }
;               AT_QKS(0, k0_);
.LBB0_1490:
	s_and_b64 vcc, exec, s[26:27]
	s_cbranch_vccz .LBB0_1463
	s_nop 6
	v_add_u32_e32 v0, s14, v158
	v_ashrrev_i32_e32 v1, 31, v0
	v_lshl_add_u64 v[146:147], s[16:17], 0, v[112:113]
	v_lshlrev_b64 v[0:1], 11, v[0:1]
	v_lshl_add_u64 v[0:1], v[146:147], 0, v[0:1]
	s_add_i32 m0, s36, 0x6000
	s_mov_b64 s[16:17], 0x100
	s_add_i32 s13, 0, 0x11000
	global_load_lds_dwordx4 v[0:1], off
	v_lshl_add_u64 v[0:1], v[142:143], 0, s[16:17]
	s_add_i32 m0, s13, s33
	s_nop 0
	global_load_lds_dwordx4 v[0:1], off
	v_lshl_add_u64 v[0:1], v[144:145], 0, s[16:17]
	s_add_i32 m0, s13, s37
	s_nop 0
	global_load_lds_dwordx4 v[0:1], off
	ds_read_b128 v[0:3], v161
	ds_read_b128 v[16:19], v161 offset:4096
	ds_read_b128 v[20:23], v160
	ds_read_b128 v[24:27], v160 offset:4096
	ds_read_b128 v[28:31], v159
	ds_read_b128 v[32:35], v159 offset:4096
	ds_read_b128 v[36:39], v141
	ds_read_b128 v[40:43], v141 offset:4096
	s_waitcnt lgkmcnt(0)
	v_mfma_f32_32x32x16_bf16 v[0:15], v[0:3], v[114:117], 0
	v_mfma_f32_32x32x16_bf16 v[64:79], v[16:19], v[114:117], 0
	v_mfma_f32_32x32x16_bf16 v[0:15], v[20:23], v[118:121], v[0:15]
	v_mfma_f32_32x32x16_bf16 v[64:79], v[24:27], v[118:121], v[64:79]
	v_mfma_f32_32x32x16_bf16 v[0:15], v[28:31], v[122:125], v[0:15]
	v_mfma_f32_32x32x16_bf16 v[64:79], v[32:35], v[122:125], v[64:79]
	v_mfma_f32_32x32x16_bf16 v[0:15], v[36:39], v[126:129], v[0:15]
	v_mfma_f32_32x32x16_bf16 v[64:79], v[40:43], v[126:129], v[64:79]
	s_nop 10
	v_max_f32_e32 v16, v1, v1
	v_max_f32_e32 v17, v0, v0
	v_max_f32_e32 v16, v17, v16
	v_max3_f32 v16, v16, v2, v3
	v_max3_f32 v16, v16, v4, v5
	v_max3_f32 v16, v16, v6, v7
	v_max3_f32 v16, v16, v8, v9
	v_max3_f32 v16, v16, v10, v11
	v_max3_f32 v16, v16, v12, v13
	v_max3_f32 v16, v16, v14, v15
	v_max3_f32 v16, v16, v64, v65
	v_max3_f32 v16, v16, v66, v67
	v_max3_f32 v16, v16, v68, v69
	v_max3_f32 v16, v16, v70, v71
	v_max3_f32 v16, v16, v72, v73
	v_max3_f32 v16, v16, v74, v75
	v_max3_f32 v16, v16, v76, v77
	v_max3_f32 v16, v16, v78, v79
	v_cmp_lt_f32_e32 vcc, s58, v16
	s_cbranch_vccz .LBB0_1493
	v_mov_b32_e32 v17, v16
	v_mov_b32_e32 v18, v16
	s_nop 1
	v_permlane32_swap_b32_e32 v17, v18
	v_cndmask_b32_e64 v17, v17, v18, s[4:5]
	v_max3_f32 v16, v16, v17, 0
	v_pk_add_f32 v[0:1], v[0:1], v[16:17] op_sel_hi:[1,0] neg_lo:[0,1] neg_hi:[0,1]
	v_pk_add_f32 v[64:65], v[64:65], v[16:17] op_sel_hi:[1,0] neg_lo:[0,1] neg_hi:[0,1]
	v_pk_add_f32 v[2:3], v[2:3], v[16:17] op_sel_hi:[1,0] neg_lo:[0,1] neg_hi:[0,1]
	v_pk_add_f32 v[66:67], v[66:67], v[16:17] op_sel_hi:[1,0] neg_lo:[0,1] neg_hi:[0,1]
	v_pk_add_f32 v[4:5], v[4:5], v[16:17] op_sel_hi:[1,0] neg_lo:[0,1] neg_hi:[0,1]
	v_pk_add_f32 v[68:69], v[68:69], v[16:17] op_sel_hi:[1,0] neg_lo:[0,1] neg_hi:[0,1]
	v_pk_add_f32 v[6:7], v[6:7], v[16:17] op_sel_hi:[1,0] neg_lo:[0,1] neg_hi:[0,1]
	v_pk_add_f32 v[70:71], v[70:71], v[16:17] op_sel_hi:[1,0] neg_lo:[0,1] neg_hi:[0,1]
	v_pk_add_f32 v[8:9], v[8:9], v[16:17] op_sel_hi:[1,0] neg_lo:[0,1] neg_hi:[0,1]
	v_pk_add_f32 v[72:73], v[72:73], v[16:17] op_sel_hi:[1,0] neg_lo:[0,1] neg_hi:[0,1]
	v_pk_add_f32 v[10:11], v[10:11], v[16:17] op_sel_hi:[1,0] neg_lo:[0,1] neg_hi:[0,1]
	v_pk_add_f32 v[74:75], v[74:75], v[16:17] op_sel_hi:[1,0] neg_lo:[0,1] neg_hi:[0,1]
	v_pk_add_f32 v[12:13], v[12:13], v[16:17] op_sel_hi:[1,0] neg_lo:[0,1] neg_hi:[0,1]
	v_exp_f32_e64 v17, -v16
	v_add_f32_e32 v164, 0, v16
	v_pk_add_f32 v[76:77], v[76:77], v[16:17] op_sel_hi:[1,0] neg_lo:[0,1] neg_hi:[0,1]
	v_pk_add_f32 v[14:15], v[14:15], v[16:17] op_sel_hi:[1,0] neg_lo:[0,1] neg_hi:[0,1]
	v_pk_add_f32 v[78:79], v[78:79], v[16:17] op_sel_hi:[1,0] neg_lo:[0,1] neg_hi:[0,1]
	v_mul_f32_e32 v96, 0, v17
	s_branch .LBB0_1494
